# NSA selected-branch unmasked pair body v3: softmax VALU of tile A interleaved under QK MFMAs of tile B, softmax of B under PV MFMAs of A
# baseline (speedup 1.0000x reference)
.LBB0_1046:
	s_andn2_b64 vcc, exec, s[22:23]
	s_cbranch_vccnz .LBB0_1048
	s_sub_i32 s22, s81, 64
	s_and_b32 s22, s22, 0xc0
	s_mulk_i32 s22, 0xa0
	v_add_u32_e32 v193, s22, v153
	ds_read_b128 v[194:197], v193
	ds_read_b128 v[198:201], v193 offset:64
	ds_read_b128 v[202:205], v193 offset:2560
	ds_read_b128 v[206:209], v193 offset:2624
	ds_read_b128 v[210:213], v193 offset:5120
	ds_read_b128 v[214:217], v193 offset:5184
	ds_read_b128 v[218:221], v193 offset:7680
	s_waitcnt lgkmcnt(14)
	v_mfma_f32_16x16x32_bf16 v[0:3], v[88:91], v[60:63], 0
	ds_read_b128 v[222:225], v193 offset:7744
	s_waitcnt lgkmcnt(13)
	v_mfma_f32_16x16x32_bf16 v[4:7], v[96:99], v[60:63], 0
	s_waitcnt lgkmcnt(11)
	v_mfma_f32_16x16x32_bf16 v[8:11], v[104:107], v[60:63], 0
	s_waitcnt lgkmcnt(9)
	v_mfma_f32_16x16x32_bf16 v[12:15], v[112:115], v[60:63], 0
	v_mfma_f32_16x16x32_bf16 v[0:3], v[92:95], v[56:59], v[0:3]
	v_mfma_f32_16x16x32_bf16 v[4:7], v[100:103], v[56:59], v[4:7]
	v_mfma_f32_16x16x32_bf16 v[8:11], v[108:111], v[56:59], v[8:11]
	s_waitcnt lgkmcnt(8)
	v_mfma_f32_16x16x32_bf16 v[12:15], v[116:119], v[56:59], v[12:15]
	s_waitcnt lgkmcnt(7)
	v_mfma_f32_16x16x32_bf16 v[240:243], v[194:197], v[60:63], 0
	ds_read_b128 v[88:91], v143 offset:40960
	ds_read_b128 v[92:95], v143 offset:43520
	v_mul_f32_e64 v226, -v146, v147
	v_cndmask_b32_e64 v226, v179, v226, s[20:21]
	v_add_f32_e32 v227, v192, v226
	v_add_f32_e32 v228, v146, v227
	v_add_f32_e32 v229, v137, v227
	v_add_f32_e32 v230, v188, v227
	v_fmamk_f32 v0, v0, 0x3e38aa3b, v227
	s_waitcnt lgkmcnt(7)
	v_mfma_f32_16x16x32_bf16 v[244:247], v[202:205], v[60:63], 0
	ds_read_b128 v[96:99], v143 offset:46080
	ds_read_b128 v[100:103], v143 offset:48640
	v_fmamk_f32 v1, v1, 0x3e38aa3b, v228
	v_fmamk_f32 v2, v2, 0x3e38aa3b, v229
	v_fmamk_f32 v3, v3, 0x3e38aa3b, v230
	v_exp_f32_e32 v0, v0
	v_exp_f32_e32 v1, v1
	v_exp_f32_e32 v2, v2
	v_exp_f32_e32 v3, v3
	s_waitcnt lgkmcnt(7)
	v_mfma_f32_16x16x32_bf16 v[248:251], v[210:213], v[60:63], 0
	ds_read_b128 v[104:107], v143 offset:41024
	ds_read_b128 v[108:111], v143 offset:43584
	v_add_f32_e32 v227, v189, v226
	v_add_f32_e32 v228, v146, v227
	v_add_f32_e32 v229, v137, v227
	v_add_f32_e32 v230, v188, v227
	v_fmamk_f32 v4, v4, 0x3e38aa3b, v227
	v_fmamk_f32 v5, v5, 0x3e38aa3b, v228
	v_fmamk_f32 v6, v6, 0x3e38aa3b, v229
	s_waitcnt lgkmcnt(7)
	v_mfma_f32_16x16x32_bf16 v[252:255], v[218:221], v[60:63], 0
	ds_read_b128 v[112:115], v143 offset:46144
	ds_read_b128 v[116:119], v143 offset:48704
	v_fmamk_f32 v7, v7, 0x3e38aa3b, v230
	v_exp_f32_e32 v4, v4
	v_exp_f32_e32 v5, v5
	v_exp_f32_e32 v6, v6
	v_exp_f32_e32 v7, v7
	v_add_f32_e32 v227, v190, v226
	v_add_f32_e32 v228, v146, v227
	v_mfma_f32_16x16x32_bf16 v[240:243], v[198:201], v[56:59], v[240:243]
	v_add_f32_e32 v229, v137, v227
	v_add_f32_e32 v230, v188, v227
	v_fmamk_f32 v8, v8, 0x3e38aa3b, v227
	v_fmamk_f32 v9, v9, 0x3e38aa3b, v228
	v_fmamk_f32 v10, v10, 0x3e38aa3b, v229
	v_fmamk_f32 v11, v11, 0x3e38aa3b, v230
	v_exp_f32_e32 v8, v8
	v_mfma_f32_16x16x32_bf16 v[244:247], v[206:209], v[56:59], v[244:247]
	v_exp_f32_e32 v9, v9
	v_exp_f32_e32 v10, v10
	v_exp_f32_e32 v11, v11
	v_add_f32_e32 v227, v191, v226
	v_add_f32_e32 v228, v146, v227
	v_add_f32_e32 v229, v137, v227
	v_add_f32_e32 v230, v188, v227
	v_mfma_f32_16x16x32_bf16 v[248:251], v[214:217], v[56:59], v[248:251]
	v_fmamk_f32 v12, v12, 0x3e38aa3b, v227
	v_fmamk_f32 v13, v13, 0x3e38aa3b, v228
	v_fmamk_f32 v14, v14, 0x3e38aa3b, v229
	v_fmamk_f32 v15, v15, 0x3e38aa3b, v230
	v_exp_f32_e32 v12, v12
	v_exp_f32_e32 v13, v13
	v_exp_f32_e32 v14, v14
	s_waitcnt lgkmcnt(8)
	v_mfma_f32_16x16x32_bf16 v[252:255], v[222:225], v[56:59], v[252:255]
	v_exp_f32_e32 v15, v15
	ds_read_b128 v[194:197], v193 offset:40960
	ds_read_b128 v[198:201], v193 offset:43520
	ds_read_b128 v[202:205], v193 offset:46080
	ds_read_b128 v[206:209], v193 offset:48640
	ds_read_b128 v[210:213], v193 offset:41024
	ds_read_b128 v[214:217], v193 offset:43584
	ds_read_b128 v[218:221], v193 offset:46144
	v_cvt_pk_bf16_f32 v226, v0, v1
	v_cvt_pk_bf16_f32 v227, v2, v3
	v_cvt_pk_bf16_f32 v228, v4, v5
	v_cvt_pk_bf16_f32 v229, v6, v7
	v_cvt_pk_bf16_f32 v230, v8, v9
	v_cvt_pk_bf16_f32 v231, v10, v11
	v_cvt_pk_bf16_f32 v232, v12, v13
	v_cvt_pk_bf16_f32 v233, v14, v15
	s_nop 1
	s_waitcnt lgkmcnt(14)
	v_mfma_f32_16x16x32_bf16 v[0:3], v[88:91], v[226:229], v[36:39]
	ds_read_b128 v[222:225], v193 offset:48704
	v_mul_f32_e64 v147, -v146, v141
	v_cndmask_b32_e64 v147, v179, v147, s[0:1]
	v_add_f32_e32 v143, v192, v147
	v_add_f32_e32 v234, v146, v143
	v_add_f32_e32 v235, v137, v143
	s_waitcnt lgkmcnt(14)
	v_mfma_f32_16x16x32_bf16 v[4:7], v[92:95], v[226:229], v[40:43]
	v_add_f32_e32 v193, v188, v143
	v_fmamk_f32 v240, v240, 0x3e38aa3b, v143
	v_fmamk_f32 v241, v241, 0x3e38aa3b, v234
	v_fmamk_f32 v242, v242, 0x3e38aa3b, v235
	v_fmamk_f32 v243, v243, 0x3e38aa3b, v193
	s_waitcnt lgkmcnt(13)
	v_mfma_f32_16x16x32_bf16 v[8:11], v[96:99], v[226:229], v[44:47]
	v_exp_f32_e32 v240, v240
	v_exp_f32_e32 v241, v241
	v_exp_f32_e32 v242, v242
	v_exp_f32_e32 v243, v243
	v_add_f32_e32 v143, v189, v147
	s_waitcnt lgkmcnt(12)
	v_mfma_f32_16x16x32_bf16 v[12:15], v[100:103], v[226:229], v[84:87]
	v_add_f32_e32 v234, v146, v143
	v_add_f32_e32 v235, v137, v143
	v_add_f32_e32 v193, v188, v143
	v_fmamk_f32 v244, v244, 0x3e38aa3b, v143
	v_fmamk_f32 v245, v245, 0x3e38aa3b, v234
	v_mov_b32_e32 v36, s28
	v_mov_b32_e32 v37, s28
	v_mov_b32_e32 v38, s28
	v_mov_b32_e32 v39, s28
	s_nop 1
	v_mfma_f32_16x16x32_bf16 v[80:83], v[36:39], v[226:229], v[32:35]
	v_fmamk_f32 v246, v246, 0x3e38aa3b, v235
	v_fmamk_f32 v247, v247, 0x3e38aa3b, v193
	v_exp_f32_e32 v244, v244
	v_exp_f32_e32 v245, v245
	v_exp_f32_e32 v246, v246
	s_waitcnt lgkmcnt(11)
	v_mfma_f32_16x16x32_bf16 v[0:3], v[104:107], v[230:233], v[0:3]
	v_exp_f32_e32 v247, v247
	v_add_f32_e32 v143, v190, v147
	v_add_f32_e32 v234, v146, v143
	v_add_f32_e32 v235, v137, v143
	v_add_f32_e32 v193, v188, v143
	s_waitcnt lgkmcnt(10)
	v_mfma_f32_16x16x32_bf16 v[4:7], v[108:111], v[230:233], v[4:7]
	v_fmamk_f32 v248, v248, 0x3e38aa3b, v143
	v_fmamk_f32 v249, v249, 0x3e38aa3b, v234
	v_fmamk_f32 v250, v250, 0x3e38aa3b, v235
	v_fmamk_f32 v251, v251, 0x3e38aa3b, v193
	v_exp_f32_e32 v248, v248
	s_waitcnt lgkmcnt(9)
	v_mfma_f32_16x16x32_bf16 v[8:11], v[112:115], v[230:233], v[8:11]
	v_exp_f32_e32 v249, v249
	v_exp_f32_e32 v250, v250
	v_exp_f32_e32 v251, v251
	v_add_f32_e32 v143, v191, v147
	v_add_f32_e32 v234, v146, v143
	s_waitcnt lgkmcnt(8)
	v_mfma_f32_16x16x32_bf16 v[12:15], v[116:119], v[230:233], v[12:15]
	v_add_f32_e32 v235, v137, v143
	v_add_f32_e32 v193, v188, v143
	v_fmamk_f32 v252, v252, 0x3e38aa3b, v143
	v_fmamk_f32 v253, v253, 0x3e38aa3b, v234
	v_fmamk_f32 v254, v254, 0x3e38aa3b, v235
	v_mfma_f32_16x16x32_bf16 v[80:83], v[36:39], v[230:233], v[80:83]
	v_fmamk_f32 v255, v255, 0x3e38aa3b, v193
	v_exp_f32_e32 v252, v252
	v_exp_f32_e32 v253, v253
	v_exp_f32_e32 v254, v254
	v_exp_f32_e32 v255, v255
	v_cvt_pk_bf16_f32 v240, v240, v241
	v_cvt_pk_bf16_f32 v241, v242, v243
	v_cvt_pk_bf16_f32 v242, v244, v245
	v_cvt_pk_bf16_f32 v243, v246, v247
	v_cvt_pk_bf16_f32 v248, v248, v249
	v_cvt_pk_bf16_f32 v249, v250, v251
	v_cvt_pk_bf16_f32 v250, v252, v253
	v_cvt_pk_bf16_f32 v251, v254, v255
	s_nop 1
	s_waitcnt lgkmcnt(7)
	v_mfma_f32_16x16x32_bf16 v[0:3], v[194:197], v[240:243], v[0:3]
	s_waitcnt lgkmcnt(6)
	v_mfma_f32_16x16x32_bf16 v[4:7], v[198:201], v[240:243], v[4:7]
	s_waitcnt lgkmcnt(5)
	v_mfma_f32_16x16x32_bf16 v[8:11], v[202:205], v[240:243], v[8:11]
	s_waitcnt lgkmcnt(4)
	v_mfma_f32_16x16x32_bf16 v[12:15], v[206:209], v[240:243], v[12:15]
	v_mfma_f32_16x16x32_bf16 v[80:83], v[36:39], v[240:243], v[80:83]
	s_waitcnt lgkmcnt(3)
	v_mfma_f32_16x16x32_bf16 v[0:3], v[210:213], v[248:251], v[0:3]
	s_waitcnt lgkmcnt(2)
	v_mfma_f32_16x16x32_bf16 v[4:7], v[214:217], v[248:251], v[4:7]
	s_waitcnt lgkmcnt(1)
	v_mfma_f32_16x16x32_bf16 v[8:11], v[218:221], v[248:251], v[8:11]
	s_waitcnt lgkmcnt(0)
	v_mfma_f32_16x16x32_bf16 v[12:15], v[222:225], v[248:251], v[12:15]
	v_mfma_f32_16x16x32_bf16 v[80:83], v[36:39], v[248:251], v[80:83]
